# compress step loop software-pipelined: next step's 20 global loads issued right after LDS staging (on top of v17)
# baseline (speedup 1.0000x reference)
; #define LAS __attribute__((address_space(3)))
; __device__ __forceinline__ void unpack8(u32x4 v, float* f) { f[0] = lo16(v.x); f[1] = hi16(v.x); f[2] = lo16(v.y); f[3] = hi16(v.y); f[4] = lo16(v.z); f[5] = hi16(v.z); f[6] = lo16(v.w); f[7] = hi16(v.w); }
; __device__ __forceinline__ void compress_item(const Params& p, int l, int item, lptr lds) {
;     int tid_ = threadIdx.x; asm volatile("" : "+v"(tid_)); const int tid = tid_, wave = __builtin_amdgcn_readfirstlane(tid >> 6), lane = tid & 63, fr = lane & 15, fq = lane >> 4;
;     const int kv = item & 1, half = (item >> 1) & 1, g = (item >> 2) & 1, b = item >> 3;
;     const bf16_t* projb = (const bf16_t*)(p.ws + WS_PROJ) + (size_t)b * SEQ * PLD;
;     const int col = (kv ? C_VC : C_KC) + g * 64;
;     const float* pe = p.in[kv ? I_PEV : I_PEK] + (size_t)l * 2048;
;     const bf16_t* w1t = (const bf16_t*)(p.ws + (kv ? WS_WC1V : WS_WC1K)); const bf16_t* w2t = (const bf16_t*)(p.ws + (kv ? WS_WC2V : WS_WC2K));
;     bf16_t* kcmp = (bf16_t*)(p.ws + WS_KCMP); bf16_t* vcmpT = (bf16_t*)(p.ws + WS_VCMPT);
;     lptr As = lds, Bs = lds + 33792, H1 = lds + 101376, W2s = lds + 118784; LAS float* Of = (LAS float*)lds;
;     const int mi = wave >> 1, nib = (wave & 1) * 4;
;     f32x4 acc[4];
; #pragma unroll
;     for (int i = 0; i < 4; ++i) acc[i] = (f32x4){0.f, 0.f, 0.f, 0.f};
;     for (int step = 0; step < 8; ++step) {
;         { const int r = tid >> 3, q = tid & 7, pp = q >> 1, e0 = (q & 1) * 32; const int cmp = half * 64 + r, pos = 16 * cmp + step * 4 + pp;
; #pragma unroll
;           for (int j = 0; j < 4; ++j) { float f[8];
;               if (pos < SEQ) unpack8(*(const u32x4*)(projb + (size_t)pos * PLD + col + e0 + j * 8), f); else {
; #pragma unroll
;                   for (int e = 0; e < 8; ++e) f[e] = 0.f; }
;               const float* pr = pe + (step * 4 + pp) * 64 + e0 + j * 8;
; #pragma unroll
;               for (int e = 0; e < 8; ++e) f[e] += pr[e];
;               *(LAS u32x4*)(As + ((size_t)r * 264 + pp * 64 + e0 + j * 8) * 2) = pack8(f); } }
;         { const int jrow = tid >> 2, k0 = (tid & 3) * 64;
; #pragma unroll
;           for (int j = 0; j < 8; ++j) *(LAS u32x4*)(Bs + ((size_t)jrow * 264 + k0 + j * 8) * 2) = *(const u32x4*)(w1t + (size_t)jrow * 2048 + step * 256 + k0 + j * 8); }
.LBB0_1516:
	v_mov_b32_e32 v46, v216
	s_and_b32 s24, s44, 1
	s_bfe_u32 s30, s44, 0x10002
	s_ashr_i32 s31, s44, 3
	s_bitcmp1_b32 s44, 0
	v_readfirstlane_b32 s37, v46
	s_mul_i32 s26, s31, 0x1320000
	s_cselect_b64 s[2:3], -1, 0
	s_bfe_u32 s36, s37, 0x10006
	s_bfe_u32 s34, s44, 0x10001
	s_mul_hi_i32 s25, s31, 0x1320000
	s_add_u32 s28, s68, s26
	s_addc_u32 s29, s69, s25
	s_cmp_eq_u32 s24, 0
	s_cselect_b64 s[24:25], -1, 0
	s_and_b64 s[26:27], s[24:25], exec
	v_readlane_b32 s40, v251, 16
	s_mov_b32 s26, 0x3900000
	v_readlane_b32 s41, v251, 17
	v_readlane_b32 s42, v251, 18
	v_readlane_b32 s43, v251, 19
	v_readlane_b32 s48, v251, 24
	v_readlane_b32 s49, v251, 25
	s_cselect_b32 s26, s26, 0x3980000
	s_movk_i32 s27, 0x1800
	s_cselect_b32 s40, s43, s49
	s_cselect_b32 s41, s42, s48
	s_cselect_b32 s38, s27, 0x1900
	s_add_u32 s26, s92, s26
	s_addc_u32 s27, s93, 0
	s_lshl_b32 s39, s30, 7
	s_lshl_b32 s42, s36, 2
	v_lshlrev_b32_e32 v0, 5, v46
	s_or_b32 s38, s39, s38
	v_and_b32_e32 v7, 32, v0
	s_add_u32 s28, s28, s38
	s_addc_u32 s29, s29, 0
	v_lshlrev_b32_e32 v0, 1, v7
	v_ashrrev_i32_e32 v2, 2, v46
	v_lshl_add_u64 v[20:21], s[28:29], 0, v[0:1]
	v_lshlrev_b32_e32 v0, 6, v46
	v_ashrrev_i32_e32 v3, 31, v2
	v_and_b32_e32 v10, 0xc0, v0
	v_lshlrev_b64 v[4:5], 12, v[2:3]
	s_movk_i32 s0, 0x108
	v_lshl_add_u64 v[4:5], s[26:27], 0, v[4:5]
	v_lshlrev_b32_e32 v0, 1, v10
	v_and_b32_e32 v43, 15, v46
	v_bfe_u32 v40, v46, 4, 2
	v_lshl_add_u64 v[22:23], v[4:5], 0, v[0:1]
	v_mul_lo_u32 v0, v2, s0
	s_ashr_i32 s26, s37, 3
	s_or_b32 s39, s42, 1
	s_or_b32 s38, s42, 2
	s_or_b32 s37, s42, 3
	v_lshlrev_b32_e32 v18, 3, v40
	v_lshl_or_b32 v4, s36, 6, v43
	v_add_lshl_u32 v10, v0, v10, 1
	v_lshl_or_b32 v0, s39, 4, v43
	v_lshl_or_b32 v13, s38, 4, v43
	v_lshl_or_b32 v14, s37, 4, v43
	v_mul_u32_u24_e32 v4, 0x108, v4
	v_mul_u32_u24_e32 v0, 0x108, v0
	v_mul_u32_u24_e32 v13, 0x108, v13
	v_mul_u32_u24_e32 v14, 0x108, v14
	v_or_b32_e32 v24, 0x80, v18
	v_ashrrev_i32_e32 v19, 3, v46
	v_add_lshl_u32 v37, v4, v24, 1
	v_add_lshl_u32 v38, v0, v24, 1
	v_add_lshl_u32 v39, v13, v24, 1
	v_add_lshl_u32 v68, v14, v24, 1
	v_or_b32_e32 v24, 0xa0, v18
	v_lshlrev_b32_e32 v8, 4, v19
	v_or_b32_e32 v3, 0xe0, v18
	v_or_b32_e32 v45, 32, v18
	v_or_b32_e32 v44, 64, v18
	v_or_b32_e32 v42, 0x60, v18
	v_add_lshl_u32 v69, v4, v24, 1
	v_add_lshl_u32 v70, v0, v24, 1
	v_add_lshl_u32 v71, v13, v24, 1
	v_add_lshl_u32 v72, v14, v24, 1
	v_or_b32_e32 v24, 0xc0, v18
	v_bfe_u32 v6, v46, 1, 2
	v_bfi_b32 v41, -16, s26, v46
	v_add_lshl_u32 v12, v0, v18, 1
	v_add_lshl_u32 v26, v0, v45, 1
	v_add_lshl_u32 v30, v0, v44, 1
	v_add_lshl_u32 v34, v0, v42, 1
	v_add_lshl_u32 v74, v0, v24, 1
	v_add_lshl_u32 v78, v0, v3, 1
	v_lshl_add_u32 v0, s34, 10, v8
	v_mul_lo_u32 v9, v19, s0
	v_mul_lo_u32 v2, v41, s0
	v_or_b32_e32 v47, v0, v6
	v_readlane_b32 s0, v254, 25
	v_and_b32_e32 v0, 1, v46
	v_readlane_b32 s1, v254, 26
	s_add_u32 s26, s41, s0
	v_lshlrev_b32_e32 v0, 7, v0
	v_add_lshl_u32 v5, v4, v3, 1
	v_add_lshl_u32 v7, v7, v9, 1
	v_lshl_add_u32 v9, v6, 7, 0
	v_add_lshl_u32 v2, v2, v18, 1
	v_add_lshl_u32 v11, v4, v18, 1
	v_add_lshl_u32 v15, v13, v18, 1
	v_add_lshl_u32 v16, v14, v18, 1
	v_add_lshl_u32 v17, v4, v45, 1
	v_add_lshl_u32 v27, v13, v45, 1
	v_add_lshl_u32 v28, v14, v45, 1
	v_add_lshl_u32 v29, v4, v44, 1
	v_add_lshl_u32 v31, v13, v44, 1
	v_add_lshl_u32 v32, v14, v44, 1
	v_add_lshl_u32 v33, v4, v42, 1
	v_add_lshl_u32 v35, v13, v42, 1
	v_add_lshl_u32 v36, v14, v42, 1
	v_add_lshl_u32 v4, v4, v24, 1
	v_add_lshl_u32 v75, v13, v24, 1
	v_add_lshl_u32 v76, v14, v24, 1
	v_add_lshl_u32 v13, v13, v3, 1
	v_add_lshl_u32 v3, v14, v3, 1
	s_addc_u32 s27, s40, s1
	v_lshl_or_b32 v0, v6, 8, v0
	v_mov_b32_e32 v14, 0
	v_lshl_add_u64 v[24:25], s[26:27], 0, v[0:1]
	s_mov_b64 s[26:27], 0
	v_add_u32_e32 v0, 0, v10
	v_add_u32_e32 v48, 0, v2
	v_add_u32_e32 v49, 0, v11
	v_add_u32_e32 v50, 0, v12
	v_add_u32_e32 v51, 0, v15
	v_add_u32_e32 v52, 0, v16
	v_add_u32_e32 v53, 0, v17
	v_add_u32_e32 v54, 0, v26
	v_add_u32_e32 v55, 0, v27
	v_add_u32_e32 v56, 0, v28
	v_add_u32_e32 v57, 0, v29
	v_add_u32_e32 v58, 0, v30
	v_add_u32_e32 v59, 0, v31
	v_add_u32_e32 v60, 0, v32
	v_add_u32_e32 v61, 0, v33
	v_add_u32_e32 v62, 0, v34
	v_add_u32_e32 v63, 0, v35
	v_add_u32_e32 v64, 0, v36
	v_add_u32_e32 v65, 0, v37
	v_add_u32_e32 v66, 0, v38
	v_add_u32_e32 v67, 0, v39
	v_add_u32_e32 v68, 0, v68
	v_add_u32_e32 v69, 0, v69
	v_add_u32_e32 v70, 0, v70
	v_add_u32_e32 v71, 0, v71
	v_add_u32_e32 v72, 0, v72
	v_add_u32_e32 v73, 0, v4
	v_add_u32_e32 v74, 0, v74
	v_add_u32_e32 v75, 0, v75
	v_add_u32_e32 v76, 0, v76
	v_add_u32_e32 v77, 0, v5
	v_add_u32_e32 v78, 0, v78
	v_add_u32_e32 v79, 0, v13
	v_add_u32_e32 v80, 0, v3
	v_add_u32_e32 v81, v9, v7
	v_mov_b32_e32 v15, v14
	v_mov_b32_e32 v16, v14
	v_mov_b32_e32 v17, v14
	v_mov_b32_e32 v10, v14
	v_mov_b32_e32 v11, v14
	v_mov_b32_e32 v12, v14
	v_mov_b32_e32 v13, v14
	v_mov_b32_e32 v6, v14
	v_mov_b32_e32 v7, v14
	v_mov_b32_e32 v8, v14
	v_mov_b32_e32 v9, v14
	v_mov_b32_e32 v2, v14
	v_mov_b32_e32 v3, v14
	v_mov_b32_e32 v4, v14
	v_mov_b32_e32 v5, v14
	v_readlane_b32 s44, v251, 20
	v_readlane_b32 s45, v251, 21
	v_readlane_b32 s46, v251, 22
	v_readlane_b32 s47, v251, 23
	v_readlane_b32 s50, v251, 26
	v_readlane_b32 s51, v251, 27
	v_readlane_b32 s52, v251, 28
	v_readlane_b32 s53, v251, 29
	v_readlane_b32 s54, v251, 30
	v_readlane_b32 s55, v251, 31
	s_movk_i32 s0, 0x800
	v_cmp_gt_i32_e32 vcc, s0, v47
	v_mad_i64_i32 v[26:27], s[28:29], v47, s70, v[20:21]
	v_lshl_add_u64 v[28:29], v[24:25], 0, s[26:27]
	v_mov_b32_e32 v90, 0
	v_mov_b32_e32 v91, 0
	v_mov_b32_e32 v92, 0
	v_mov_b32_e32 v93, 0
	v_mov_b32_e32 v94, 0
	v_mov_b32_e32 v95, 0
	v_mov_b32_e32 v96, 0
	v_mov_b32_e32 v97, 0
	v_mov_b32_e32 v98, 0
	v_mov_b32_e32 v99, 0
	v_mov_b32_e32 v100, 0
	v_mov_b32_e32 v101, 0
	v_mov_b32_e32 v102, 0
	v_mov_b32_e32 v103, 0
	v_mov_b32_e32 v104, 0
	v_mov_b32_e32 v105, 0
	s_and_saveexec_b64 s[28:29], vcc
	global_load_dwordx4 v[90:93], v[26:27], off
	global_load_dwordx4 v[94:97], v[26:27], off offset:16
	global_load_dwordx4 v[98:101], v[26:27], off offset:32
	global_load_dwordx4 v[102:105], v[26:27], off offset:48
	s_or_b64 exec, exec, s[28:29]
	global_load_dwordx4 v[140:143], v[28:29], off
	global_load_dwordx4 v[144:147], v[28:29], off offset:16
	global_load_dwordx4 v[148:151], v[28:29], off offset:32
	global_load_dwordx4 v[152:155], v[28:29], off offset:48
	global_load_dwordx4 v[156:159], v[28:29], off offset:64
	global_load_dwordx4 v[160:163], v[28:29], off offset:80
	global_load_dwordx4 v[164:167], v[28:29], off offset:96
	global_load_dwordx4 v[168:171], v[28:29], off offset:112
	global_load_dwordx4 v[106:109], v[22:23], off
	global_load_dwordx4 v[110:113], v[22:23], off offset:16
	global_load_dwordx4 v[114:117], v[22:23], off offset:32
	global_load_dwordx4 v[118:121], v[22:23], off offset:48
	global_load_dwordx4 v[122:125], v[22:23], off offset:64
	global_load_dwordx4 v[172:175], v[22:23], off offset:80
	global_load_dwordx4 v[176:179], v[22:23], off offset:96
	global_load_dwordx4 v[180:183], v[22:23], off offset:112
	s_branch .LBB0_1518

; #define LAS __attribute__((address_space(3)))
; __device__ __forceinline__ void unpack8(u32x4 v, float* f) { f[0] = lo16(v.x); f[1] = hi16(v.x); f[2] = lo16(v.y); f[3] = hi16(v.y); f[4] = lo16(v.z); f[5] = hi16(v.z); f[6] = lo16(v.w); f[7] = hi16(v.w); }
; __device__ __forceinline__ u32x4 pack8(const float* f) { u32x4 o; o.x = pk2(f[0], f[1]); o.y = pk2(f[2], f[3]); o.z = pk2(f[4], f[5]); o.w = pk2(f[6], f[7]); return o; }
; __device__ __forceinline__ void compress_item(const Params& p, int l, int item, lptr lds) {
;     ...
;         { const int r = tid >> 3, q = tid & 7, pp = q >> 1, e0 = (q & 1) * 32; const int cmp = half * 64 + r, pos = 16 * cmp + step * 4 + pp;
; #pragma unroll
;           for (int j = 0; j < 4; ++j) { float f[8];
;               if (pos < SEQ) unpack8(*(const u32x4*)(projb + (size_t)pos * PLD + col + e0 + j * 8), f); else {
; #pragma unroll
;                   for (int e = 0; e < 8; ++e) f[e] = 0.f; }
;               const float* pr = pe + (step * 4 + pp) * 64 + e0 + j * 8;
; #pragma unroll
;               for (int e = 0; e < 8; ++e) f[e] += pr[e];
;               *(LAS u32x4*)(As + ((size_t)r * 264 + pp * 64 + e0 + j * 8) * 2) = pack8(f); } }
;         { const int jrow = tid >> 2, k0 = (tid & 3) * 64;
; #pragma unroll
;           for (int j = 0; j < 8; ++j) *(LAS u32x4*)(Bs + ((size_t)jrow * 264 + k0 + j * 8) * 2) = *(const u32x4*)(w1t + (size_t)jrow * 2048 + step * 256 + k0 + j * 8); }
.LBB0_1518:
	s_waitcnt vmcnt(14)
	v_lshlrev_b32_e32 v126, 16, v90
	v_and_b32_e32 v127, 0xffff0000, v90
	v_lshlrev_b32_e32 v128, 16, v91
	v_and_b32_e32 v129, 0xffff0000, v91
	v_lshlrev_b32_e32 v130, 16, v92
	v_and_b32_e32 v131, 0xffff0000, v92
	v_lshlrev_b32_e32 v132, 16, v93
	v_and_b32_e32 v133, 0xffff0000, v93
	v_pk_add_f32 v[126:127], v[126:127], v[140:141]
	v_pk_add_f32 v[128:129], v[128:129], v[142:143]
	v_pk_add_f32 v[130:131], v[130:131], v[144:145]
	v_pk_add_f32 v[132:133], v[132:133], v[146:147]
	v_cvt_pk_bf16_f32 v126, v126, v127
	v_cvt_pk_bf16_f32 v127, v128, v129
	v_cvt_pk_bf16_f32 v128, v130, v131
	v_cvt_pk_bf16_f32 v129, v132, v133
	ds_write_b128 v81, v[126:129]
	s_waitcnt vmcnt(12)
	v_lshlrev_b32_e32 v126, 16, v94
	v_and_b32_e32 v127, 0xffff0000, v94
	v_lshlrev_b32_e32 v128, 16, v95
	v_and_b32_e32 v129, 0xffff0000, v95
	v_lshlrev_b32_e32 v130, 16, v96
	v_and_b32_e32 v131, 0xffff0000, v96
	v_lshlrev_b32_e32 v132, 16, v97
	v_and_b32_e32 v133, 0xffff0000, v97
	v_pk_add_f32 v[126:127], v[126:127], v[148:149]
	v_pk_add_f32 v[128:129], v[128:129], v[150:151]
	v_pk_add_f32 v[130:131], v[130:131], v[152:153]
	v_pk_add_f32 v[132:133], v[132:133], v[154:155]
	v_cvt_pk_bf16_f32 v126, v126, v127
	v_cvt_pk_bf16_f32 v127, v128, v129
	v_cvt_pk_bf16_f32 v128, v130, v131
	v_cvt_pk_bf16_f32 v129, v132, v133
	ds_write_b128 v81, v[126:129] offset:16
	s_waitcnt vmcnt(10)
	v_lshlrev_b32_e32 v126, 16, v98
	v_and_b32_e32 v127, 0xffff0000, v98
	v_lshlrev_b32_e32 v128, 16, v99
	v_and_b32_e32 v129, 0xffff0000, v99
	v_lshlrev_b32_e32 v130, 16, v100
	v_and_b32_e32 v131, 0xffff0000, v100
	v_lshlrev_b32_e32 v132, 16, v101
	v_and_b32_e32 v133, 0xffff0000, v101
	v_pk_add_f32 v[126:127], v[126:127], v[156:157]
	v_pk_add_f32 v[128:129], v[128:129], v[158:159]
	v_pk_add_f32 v[130:131], v[130:131], v[160:161]
	v_pk_add_f32 v[132:133], v[132:133], v[162:163]
	v_cvt_pk_bf16_f32 v126, v126, v127
	v_cvt_pk_bf16_f32 v127, v128, v129
	v_cvt_pk_bf16_f32 v128, v130, v131
	v_cvt_pk_bf16_f32 v129, v132, v133
	ds_write_b128 v81, v[126:129] offset:32
	s_waitcnt vmcnt(8)
	v_lshlrev_b32_e32 v126, 16, v102
	v_and_b32_e32 v127, 0xffff0000, v102
	v_lshlrev_b32_e32 v128, 16, v103
	v_and_b32_e32 v129, 0xffff0000, v103
	v_lshlrev_b32_e32 v130, 16, v104
	v_and_b32_e32 v131, 0xffff0000, v104
	v_lshlrev_b32_e32 v132, 16, v105
	v_and_b32_e32 v133, 0xffff0000, v105
	v_pk_add_f32 v[126:127], v[126:127], v[164:165]
	v_pk_add_f32 v[128:129], v[128:129], v[166:167]
	v_pk_add_f32 v[130:131], v[130:131], v[168:169]
	v_pk_add_f32 v[132:133], v[132:133], v[170:171]
	v_cvt_pk_bf16_f32 v126, v126, v127
	v_cvt_pk_bf16_f32 v127, v128, v129
	v_cvt_pk_bf16_f32 v128, v130, v131
	v_cvt_pk_bf16_f32 v129, v132, v133
	ds_write_b128 v81, v[126:129] offset:48
	s_waitcnt vmcnt(0)
	ds_write_b128 v0, v[106:109] offset:33792
	ds_write_b128 v0, v[110:113] offset:33808
	ds_write_b128 v0, v[114:117] offset:33824
	ds_write_b128 v0, v[118:121] offset:33840
	ds_write_b128 v0, v[122:125] offset:33856
	ds_write_b128 v0, v[172:175] offset:33872
	ds_write_b128 v0, v[176:179] offset:33888
	ds_write_b128 v0, v[180:183] offset:33904
	s_add_u32 s26, s26, 0x400
	s_addc_u32 s27, s27, 0
	s_mov_b64 s[28:29], 0x200
	v_add_u32_e32 v47, 4, v47
	v_lshl_add_u64 v[22:23], v[22:23], 0, s[28:29]
	s_cmpk_eq_i32 s26, 0x2000
	s_cbranch_scc1 .Lmy_cmp_nopf
	s_movk_i32 s0, 0x800
	v_cmp_gt_i32_e32 vcc, s0, v47
	v_mad_i64_i32 v[26:27], s[28:29], v47, s70, v[20:21]
	v_lshl_add_u64 v[28:29], v[24:25], 0, s[26:27]
	v_mov_b32_e32 v90, 0
	v_mov_b32_e32 v91, 0
	v_mov_b32_e32 v92, 0
	v_mov_b32_e32 v93, 0
	v_mov_b32_e32 v94, 0
	v_mov_b32_e32 v95, 0
	v_mov_b32_e32 v96, 0
	v_mov_b32_e32 v97, 0
	v_mov_b32_e32 v98, 0
	v_mov_b32_e32 v99, 0
	v_mov_b32_e32 v100, 0
	v_mov_b32_e32 v101, 0
	v_mov_b32_e32 v102, 0
	v_mov_b32_e32 v103, 0
	v_mov_b32_e32 v104, 0
	v_mov_b32_e32 v105, 0
	s_and_saveexec_b64 s[28:29], vcc
	global_load_dwordx4 v[90:93], v[26:27], off
	global_load_dwordx4 v[94:97], v[26:27], off offset:16
	global_load_dwordx4 v[98:101], v[26:27], off offset:32
	global_load_dwordx4 v[102:105], v[26:27], off offset:48
	s_or_b64 exec, exec, s[28:29]
	global_load_dwordx4 v[140:143], v[28:29], off
	global_load_dwordx4 v[144:147], v[28:29], off offset:16
	global_load_dwordx4 v[148:151], v[28:29], off offset:32
	global_load_dwordx4 v[152:155], v[28:29], off offset:48
	global_load_dwordx4 v[156:159], v[28:29], off offset:64
	global_load_dwordx4 v[160:163], v[28:29], off offset:80
	global_load_dwordx4 v[164:167], v[28:29], off offset:96
	global_load_dwordx4 v[168:171], v[28:29], off offset:112
	global_load_dwordx4 v[106:109], v[22:23], off
	global_load_dwordx4 v[110:113], v[22:23], off offset:16
	global_load_dwordx4 v[114:117], v[22:23], off offset:32
	global_load_dwordx4 v[118:121], v[22:23], off offset:48
	global_load_dwordx4 v[122:125], v[22:23], off offset:64
	global_load_dwordx4 v[172:175], v[22:23], off offset:80
	global_load_dwordx4 v[176:179], v[22:23], off offset:96
	global_load_dwordx4 v[180:183], v[22:23], off offset:112
.Lmy_cmp_nopf:
	s_cmpk_eq_i32 s26, 0x2000
	s_branch .Lmy_cmp_mfma
